# comb2 + attention epilogue DPP instead of bpermute + K-tile LDS writes moved ahead of the first barrier
# speedup vs baseline: 1.0099x; 1.0003x over previous
.Latta_539:
	s_waitcnt vmcnt(0)
	ds_write_b128 v224, v[186:189] offset:32768
	ds_write_b128 v224, v[190:193] offset:40960
	s_barrier
	v_cmp_gt_f32_e32 vcc, 1.0, v233
	ds_write_b128 v216, v[178:181]
	ds_write_b128 v217, v[182:185]
	s_cbranch_vccz .Latta_543
	s_and_saveexec_b64 s[10:11], s[2:3]
	ds_write_b32 v227, v233 offset:128
	s_or_b64 exec, exec, s[10:11]
	s_waitcnt lgkmcnt(0)
	ds_read_b128 v[234:237], v225 offset:224
	ds_read_b128 v[238:241], v225 offset:192
	ds_read_b128 v[246:249], v225 offset:160
	ds_read_b128 v[250:253], v225 offset:128
	s_waitcnt lgkmcnt(3)
	v_pk_mul_f32 v[48:49], v[48:49], v[236:237]
	s_waitcnt lgkmcnt(2)
	v_pk_mul_f32 v[44:45], v[44:45], v[240:241]
	s_waitcnt lgkmcnt(1)
	v_pk_mul_f32 v[40:41], v[40:41], v[248:249]
	s_waitcnt lgkmcnt(0)
	v_pk_mul_f32 v[36:37], v[36:37], v[252:253]
	v_pk_mul_f32 v[46:47], v[46:47], v[234:235]
	v_pk_mul_f32 v[42:43], v[42:43], v[238:239]
	v_pk_mul_f32 v[38:39], v[38:39], v[246:247]
	v_pk_mul_f32 v[34:35], v[34:35], v[250:251]
	v_pk_mul_f32 v[64:65], v[64:65], v[236:237]
	v_pk_mul_f32 v[60:61], v[60:61], v[240:241]
	v_pk_mul_f32 v[56:57], v[56:57], v[248:249]
	v_pk_mul_f32 v[52:53], v[52:53], v[252:253]
	v_pk_mul_f32 v[62:63], v[62:63], v[234:235]
	v_pk_mul_f32 v[58:59], v[58:59], v[238:239]
	v_pk_mul_f32 v[54:55], v[54:55], v[246:247]
	v_pk_mul_f32 v[50:51], v[50:51], v[250:251]
	v_pk_mul_f32 v[32:33], v[32:33], v[236:237]
	v_pk_mul_f32 v[28:29], v[28:29], v[240:241]
	v_pk_mul_f32 v[24:25], v[24:25], v[248:249]
	v_pk_mul_f32 v[20:21], v[20:21], v[252:253]
	v_pk_mul_f32 v[30:31], v[30:31], v[234:235]
	v_pk_mul_f32 v[26:27], v[26:27], v[238:239]
	v_pk_mul_f32 v[22:23], v[22:23], v[246:247]
	v_pk_mul_f32 v[18:19], v[18:19], v[250:251]
	v_pk_mul_f32 v[16:17], v[16:17], v[236:237]
	v_pk_mul_f32 v[12:13], v[12:13], v[240:241]
	v_pk_mul_f32 v[8:9], v[8:9], v[248:249]
	v_pk_mul_f32 v[4:5], v[4:5], v[252:253]
	v_pk_mul_f32 v[14:15], v[14:15], v[234:235]
	v_pk_mul_f32 v[10:11], v[10:11], v[238:239]
	v_pk_mul_f32 v[6:7], v[6:7], v[246:247]
	v_pk_mul_f32 v[2:3], v[2:3], v[250:251]

.Latta_555:
	s_andn2_b64 vcc, exec, s[70:71]
	s_cbranch_vccnz .Latta_9050
	s_waitcnt vmcnt(0)
	ds_write_b128 v224, v[186:189] offset:49152
	ds_write_b128 v224, v[190:193] offset:57344
.Latta_9050:
	s_barrier
	s_cbranch_vccnz .Latta_557
	ds_write_b128 v216, v[178:181] offset:16384
	ds_write_b128 v217, v[182:185] offset:16384

; __device__ __forceinline__ unsigned cvt_pk_bf16(float lo, float hi) { unsigned r; asm volatile("v_cvt_pk_bf16_f32 %0, %1, %2" : "=v"(r) : "v"(lo), "v"(hi)); return r; }
; __device__ __forceinline__ int crow(int r, int hi) { return (r & 3) + 8 * (r >> 2) + 4 * hi; }
; #define SBAR() __builtin_amdgcn_sched_barrier(0)
; __device__ __forceinline__ int crow(int r, int hi) { return (r & 3) + 8 * (r >> 2) + 4 * hi; }
; #define SEAM_K0() do { VMWN(8); SWRITE_HK(0); SBAR(); } while (0)
; __device__ __forceinline__ void block(const BlockRef& cur, const BlockRef& nxt, lptr lds, Seam& S) {
;     ...
;     SBAR(); SEAM_K0();
;     if (hi == 0) li_l[r32] = l_reg; asm volatile("s_waitcnt lgkmcnt(0)" ::: "memory");
;     float rli[16];
; #pragma unroll
;     for (int r = 0; r < 16; ++r) rli[r] = __builtin_amdgcn_rcpf(li_l[crow(r, hi)]);
;     bf16* Ow = cur.O + (size_t)(wid * QBLK) * KM;
; #pragma unroll
;     for (int r = 0; r < 16; ++r) { const int orow = crow(r, hi);
; #pragma unroll
;         for (int d0 = 0; d0 < 4; ++d0) { const float v = o[d0][r] * rli[r];
;             const float vn = __shfl_xor(v, 1);
;             if ((r32 & 1) == 0) *(unsigned*)(Ow + (size_t)orow * KM + d0 * 32 + r32) = cvt_pk_bf16(v, vn); } }
.LBB0_574:
	s_waitcnt vmcnt(8)
	s_waitcnt vmcnt(9)
	ds_write_b128 v224, v[170:173] offset:32768
	s_waitcnt vmcnt(8)
	ds_write_b128 v224, v[174:177] offset:40960
	s_and_saveexec_b64 s[8:9], s[2:3]
	ds_write_b32 v227, v230
	s_or_b64 exec, exec, s[8:9]
	s_waitcnt lgkmcnt(0)
	ds_read_b128 v[78:81], v225
	v_xor_b32_e32 v82, 1, v215
	ds_read_b128 v[74:77], v225 offset:32
	ds_read_b128 v[70:73], v225 offset:64
	ds_read_b128 v[66:69], v225 offset:96
	s_mul_hi_u32 s7, s1, 0x6000
	s_mulk_i32 s1, 0x6000
	s_waitcnt lgkmcnt(3)
	v_rcp_f32_e32 v85, v78
	v_and_b32_e32 v78, 64, v215
	v_add_u32_e32 v83, 64, v78
	v_cmp_lt_i32_e32 vcc, v82, v83
	v_mul_f32_e32 v34, v34, v85
	s_add_u32 s6, s80, s1
	v_cndmask_b32_e32 v82, v215, v82, vcc
	v_lshlrev_b32_e32 v84, 2, v82
	s_nop 3
	v_mov_b32_dpp v86, v34 quad_perm:[1,0,3,2] row_mask:0xf bank_mask:0xf
	s_addc_u32 s7, s81, s7
	v_lshl_add_u64 v[82:83], s[6:7], 0, v[194:195]
	v_lshl_add_u64 v[82:83], v[82:83], 0, v[202:203]
	s_and_saveexec_b64 s[8:9], s[4:5]
	s_cbranch_execz .LBB0_578
	s_waitcnt lgkmcnt(0)
	v_cvt_pk_bf16_f32 v34, v34, v86
	global_store_dword v[82:83], v34, off
.LBB0_578:
	s_or_b64 exec, exec, s[8:9]
	v_mul_f32_e32 v34, v50, v85
	s_nop 3
	v_mov_b32_dpp v50, v34 quad_perm:[1,0,3,2] row_mask:0xf bank_mask:0xf
	s_and_saveexec_b64 s[8:9], s[4:5]
	s_cbranch_execz .LBB0_580
	s_waitcnt lgkmcnt(0)
	v_cvt_pk_bf16_f32 v34, v34, v50
	global_store_dword v[82:83], v34, off offset:64
.LBB0_580:
	s_or_b64 exec, exec, s[8:9]
	v_mul_f32_e32 v18, v18, v85
	s_nop 3
	v_mov_b32_dpp v34, v18 quad_perm:[1,0,3,2] row_mask:0xf bank_mask:0xf
	s_and_saveexec_b64 s[8:9], s[4:5]
	s_cbranch_execz .LBB0_582
	s_waitcnt lgkmcnt(0)
	v_cvt_pk_bf16_f32 v18, v18, v34
	global_store_dword v[82:83], v18, off offset:128
.LBB0_582:
	s_or_b64 exec, exec, s[8:9]
	v_mul_f32_e32 v2, v2, v85
	s_nop 3
	v_mov_b32_dpp v18, v2 quad_perm:[1,0,3,2] row_mask:0xf bank_mask:0xf
	s_and_saveexec_b64 s[8:9], s[4:5]
	s_cbranch_execz .LBB0_584
	s_waitcnt lgkmcnt(0)
	v_cvt_pk_bf16_f32 v2, v2, v18
	global_store_dword v[82:83], v2, off offset:192
.LBB0_584:
	s_or_b64 exec, exec, s[8:9]
	v_rcp_f32_e32 v2, v79
	s_waitcnt lgkmcnt(0)
	v_mul_f32_e32 v18, v35, v2
	s_nop 3
	v_mov_b32_dpp v34, v18 quad_perm:[1,0,3,2] row_mask:0xf bank_mask:0xf
	s_and_saveexec_b64 s[8:9], s[4:5]
	s_cbranch_execz .LBB0_586
	s_waitcnt lgkmcnt(0)
	v_cvt_pk_bf16_f32 v18, v18, v34
	v_add_co_u32_e32 v34, vcc, 0x6000, v82
	s_nop 1
	v_addc_co_u32_e32 v35, vcc, 0, v83, vcc
	global_store_dword v[34:35], v18, off
.LBB0_586:
	s_or_b64 exec, exec, s[8:9]
	v_mul_f32_e32 v18, v51, v2
	s_waitcnt lgkmcnt(0)
	s_nop 3
	v_mov_b32_dpp v34, v18 quad_perm:[1,0,3,2] row_mask:0xf bank_mask:0xf
	s_and_saveexec_b64 s[8:9], s[4:5]
	s_cbranch_execz .LBB0_588
	s_waitcnt lgkmcnt(0)
	v_cvt_pk_bf16_f32 v18, v18, v34
	v_add_co_u32_e32 v34, vcc, 0x6000, v82
	s_nop 1
	v_addc_co_u32_e32 v35, vcc, 0, v83, vcc
	global_store_dword v[34:35], v18, off offset:64
.LBB0_588:
	s_or_b64 exec, exec, s[8:9]
	v_mul_f32_e32 v18, v19, v2
	s_nop 3
	v_mov_b32_dpp v19, v18 quad_perm:[1,0,3,2] row_mask:0xf bank_mask:0xf
	s_and_saveexec_b64 s[8:9], s[4:5]
	s_cbranch_execz .LBB0_590
	s_waitcnt lgkmcnt(0)
	v_cvt_pk_bf16_f32 v34, v18, v19
	v_add_co_u32_e32 v18, vcc, 0x6000, v82
	s_nop 1
	v_addc_co_u32_e32 v19, vcc, 0, v83, vcc
	global_store_dword v[18:19], v34, off offset:128
.LBB0_590:
	s_or_b64 exec, exec, s[8:9]
	v_mul_f32_e32 v2, v3, v2
	s_nop 3
	v_mov_b32_dpp v3, v2 quad_perm:[1,0,3,2] row_mask:0xf bank_mask:0xf
	s_and_saveexec_b64 s[8:9], s[4:5]
	s_cbranch_execz .LBB0_592
	s_waitcnt lgkmcnt(0)
	v_cvt_pk_bf16_f32 v18, v2, v3
	v_add_co_u32_e32 v2, vcc, 0x6000, v82
	s_nop 1
	v_addc_co_u32_e32 v3, vcc, 0, v83, vcc
	global_store_dword v[2:3], v18, off offset:192
.LBB0_592:
	s_or_b64 exec, exec, s[8:9]
	v_rcp_f32_e32 v2, v80
	s_waitcnt lgkmcnt(0)
	v_mul_f32_e32 v3, v36, v2
	s_nop 3
	v_mov_b32_dpp v18, v3 quad_perm:[1,0,3,2] row_mask:0xf bank_mask:0xf
	s_and_saveexec_b64 s[8:9], s[4:5]
	s_cbranch_execz .LBB0_594
	s_waitcnt lgkmcnt(0)
	v_cvt_pk_bf16_f32 v3, v3, v18
	v_add_co_u32_e32 v18, vcc, 0xc000, v82
	s_nop 1
	v_addc_co_u32_e32 v19, vcc, 0, v83, vcc
	global_store_dword v[18:19], v3, off
.LBB0_594:
	s_or_b64 exec, exec, s[8:9]
	v_mul_f32_e32 v3, v52, v2
	s_waitcnt lgkmcnt(0)
	s_nop 3
	v_mov_b32_dpp v18, v3 quad_perm:[1,0,3,2] row_mask:0xf bank_mask:0xf
	s_and_saveexec_b64 s[8:9], s[4:5]
	s_cbranch_execz .LBB0_596
	s_waitcnt lgkmcnt(0)
	v_cvt_pk_bf16_f32 v3, v3, v18
	v_add_co_u32_e32 v18, vcc, 0xc000, v82
	s_nop 1
	v_addc_co_u32_e32 v19, vcc, 0, v83, vcc
	global_store_dword v[18:19], v3, off offset:64
.LBB0_596:
	s_or_b64 exec, exec, s[8:9]
	v_mul_f32_e32 v3, v20, v2
	s_waitcnt lgkmcnt(0)
	s_nop 3
	v_mov_b32_dpp v18, v3 quad_perm:[1,0,3,2] row_mask:0xf bank_mask:0xf
	s_and_saveexec_b64 s[8:9], s[4:5]
	s_cbranch_execz .LBB0_598
	s_waitcnt lgkmcnt(0)
	v_cvt_pk_bf16_f32 v3, v3, v18
	v_add_co_u32_e32 v18, vcc, 0xc000, v82
	s_nop 1
	v_addc_co_u32_e32 v19, vcc, 0, v83, vcc
	global_store_dword v[18:19], v3, off offset:128
.LBB0_598:
	s_or_b64 exec, exec, s[8:9]
	v_mul_f32_e32 v2, v4, v2
	s_nop 3
	v_mov_b32_dpp v3, v2 quad_perm:[1,0,3,2] row_mask:0xf bank_mask:0xf
	s_and_saveexec_b64 s[8:9], s[4:5]
	s_cbranch_execz .LBB0_600
	s_waitcnt lgkmcnt(0)
	v_cvt_pk_bf16_f32 v4, v2, v3
	v_add_co_u32_e32 v2, vcc, 0xc000, v82
	s_nop 1
	v_addc_co_u32_e32 v3, vcc, 0, v83, vcc
	global_store_dword v[2:3], v4, off offset:192
.LBB0_600:
	s_or_b64 exec, exec, s[8:9]
	v_rcp_f32_e32 v2, v81
	s_waitcnt lgkmcnt(0)
	v_mul_f32_e32 v3, v37, v2
	s_nop 3
	v_mov_b32_dpp v4, v3 quad_perm:[1,0,3,2] row_mask:0xf bank_mask:0xf
	s_and_saveexec_b64 s[8:9], s[4:5]
	s_cbranch_execz .LBB0_602
	v_add_co_u32_e32 v18, vcc, 0x12000, v82
	s_waitcnt lgkmcnt(0)
	v_cvt_pk_bf16_f32 v3, v3, v4
	s_nop 0
	v_addc_co_u32_e32 v19, vcc, 0, v83, vcc
	global_store_dword v[18:19], v3, off
; __device__ __forceinline__ unsigned cvt_pk_bf16(float lo, float hi) { unsigned r; asm volatile("v_cvt_pk_bf16_f32 %0, %1, %2" : "=v"(r) : "v"(lo), "v"(hi)); return r; }
; __device__ __forceinline__ int crow(int r, int hi) { return (r & 3) + 8 * (r >> 2) + 4 * hi; }
; __device__ __forceinline__ int crow(int r, int hi) { return (r & 3) + 8 * (r >> 2) + 4 * hi; }
; __device__ __forceinline__ void block(const BlockRef& cur, const BlockRef& nxt, lptr lds, Seam& S) {
;     ...
;     for (int r = 0; r < 16; ++r) { const int orow = crow(r, hi);
; #pragma unroll
;         for (int d0 = 0; d0 < 4; ++d0) { const float v = o[d0][r] * rli[r];
;             const float vn = __shfl_xor(v, 1);
;             if ((r32 & 1) == 0) *(unsigned*)(Ow + (size_t)orow * KM + d0 * 32 + r32) = cvt_pk_bf16(v, vn); } }
.LBB0_602:
	s_or_b64 exec, exec, s[8:9]
	v_mul_f32_e32 v3, v53, v2
	s_waitcnt lgkmcnt(0)
	s_nop 3
	v_mov_b32_dpp v4, v3 quad_perm:[1,0,3,2] row_mask:0xf bank_mask:0xf
	s_and_saveexec_b64 s[8:9], s[4:5]
	s_cbranch_execz .LBB0_604
	v_add_co_u32_e32 v18, vcc, 0x12000, v82
	s_waitcnt lgkmcnt(0)
	v_cvt_pk_bf16_f32 v3, v3, v4
	s_nop 0
	v_addc_co_u32_e32 v19, vcc, 0, v83, vcc
	global_store_dword v[18:19], v3, off offset:64
.LBB0_604:
	s_or_b64 exec, exec, s[8:9]
	v_mul_f32_e32 v3, v21, v2
	s_waitcnt lgkmcnt(0)
	s_nop 3
	v_mov_b32_dpp v4, v3 quad_perm:[1,0,3,2] row_mask:0xf bank_mask:0xf
	s_and_saveexec_b64 s[8:9], s[4:5]
	s_cbranch_execz .LBB0_606
	v_add_co_u32_e32 v18, vcc, 0x12000, v82
	s_waitcnt lgkmcnt(0)
	v_cvt_pk_bf16_f32 v3, v3, v4
	s_nop 0
	v_addc_co_u32_e32 v19, vcc, 0, v83, vcc
	global_store_dword v[18:19], v3, off offset:128
.LBB0_606:
	s_or_b64 exec, exec, s[8:9]
	v_mul_f32_e32 v2, v5, v2
	s_nop 3
	v_mov_b32_dpp v3, v2 quad_perm:[1,0,3,2] row_mask:0xf bank_mask:0xf
	s_and_saveexec_b64 s[8:9], s[4:5]
	s_cbranch_execz .LBB0_608
	s_waitcnt lgkmcnt(0)
	v_cvt_pk_bf16_f32 v4, v2, v3
	v_add_co_u32_e32 v2, vcc, 0x12000, v82
	s_nop 1
	v_addc_co_u32_e32 v3, vcc, 0, v83, vcc
	global_store_dword v[2:3], v4, off offset:192
.LBB0_608:
	s_or_b64 exec, exec, s[8:9]
	v_rcp_f32_e32 v2, v74
	s_waitcnt lgkmcnt(0)
	v_mul_f32_e32 v3, v38, v2
	s_nop 3
	v_mov_b32_dpp v4, v3 quad_perm:[1,0,3,2] row_mask:0xf bank_mask:0xf
	s_and_saveexec_b64 s[8:9], s[4:5]
	s_cbranch_execz .LBB0_610
	s_waitcnt lgkmcnt(0)
	v_cvt_pk_bf16_f32 v3, v3, v4
	v_add_co_u32_e32 v4, vcc, 0x30000, v82
	s_nop 1
	v_addc_co_u32_e32 v5, vcc, 0, v83, vcc
	global_store_dword v[4:5], v3, off
.LBB0_610:
	s_or_b64 exec, exec, s[8:9]
	v_mul_f32_e32 v3, v54, v2
	s_waitcnt lgkmcnt(0)
	s_nop 3
	v_mov_b32_dpp v4, v3 quad_perm:[1,0,3,2] row_mask:0xf bank_mask:0xf
	s_and_saveexec_b64 s[8:9], s[4:5]
	s_cbranch_execz .LBB0_612
	s_waitcnt lgkmcnt(0)
	v_cvt_pk_bf16_f32 v3, v3, v4
	v_add_co_u32_e32 v4, vcc, 0x30000, v82
	s_nop 1
	v_addc_co_u32_e32 v5, vcc, 0, v83, vcc
	global_store_dword v[4:5], v3, off offset:64
.LBB0_612:
	s_or_b64 exec, exec, s[8:9]
	v_mul_f32_e32 v3, v22, v2
	s_waitcnt lgkmcnt(0)
	s_nop 3
	v_mov_b32_dpp v4, v3 quad_perm:[1,0,3,2] row_mask:0xf bank_mask:0xf
	s_and_saveexec_b64 s[8:9], s[4:5]
	s_cbranch_execz .LBB0_614
	s_waitcnt lgkmcnt(0)
	v_cvt_pk_bf16_f32 v3, v3, v4
	v_add_co_u32_e32 v4, vcc, 0x30000, v82
	s_nop 1
	v_addc_co_u32_e32 v5, vcc, 0, v83, vcc
	global_store_dword v[4:5], v3, off offset:128
.LBB0_614:
	s_or_b64 exec, exec, s[8:9]
	v_mul_f32_e32 v2, v6, v2
	s_nop 3
	v_mov_b32_dpp v3, v2 quad_perm:[1,0,3,2] row_mask:0xf bank_mask:0xf
	s_and_saveexec_b64 s[8:9], s[4:5]
	s_cbranch_execz .LBB0_616
	s_waitcnt lgkmcnt(0)
	v_cvt_pk_bf16_f32 v4, v2, v3
	v_add_co_u32_e32 v2, vcc, 0x30000, v82
	s_nop 1
	v_addc_co_u32_e32 v3, vcc, 0, v83, vcc
	global_store_dword v[2:3], v4, off offset:192
.LBB0_616:
	s_or_b64 exec, exec, s[8:9]
	v_rcp_f32_e32 v2, v75
	s_waitcnt lgkmcnt(0)
	v_mul_f32_e32 v3, v39, v2
	s_nop 3
	v_mov_b32_dpp v4, v3 quad_perm:[1,0,3,2] row_mask:0xf bank_mask:0xf
	s_and_saveexec_b64 s[8:9], s[4:5]
	s_cbranch_execz .LBB0_618
	s_waitcnt lgkmcnt(0)
	v_cvt_pk_bf16_f32 v3, v3, v4
	v_add_co_u32_e32 v4, vcc, 0x36000, v82
	s_nop 1
	v_addc_co_u32_e32 v5, vcc, 0, v83, vcc
	global_store_dword v[4:5], v3, off
.LBB0_618:
	s_or_b64 exec, exec, s[8:9]
	v_mul_f32_e32 v3, v55, v2
	s_waitcnt lgkmcnt(0)
	s_nop 3
	v_mov_b32_dpp v4, v3 quad_perm:[1,0,3,2] row_mask:0xf bank_mask:0xf
	s_and_saveexec_b64 s[8:9], s[4:5]
	s_cbranch_execz .LBB0_620
	s_waitcnt lgkmcnt(0)
	v_cvt_pk_bf16_f32 v3, v3, v4
	v_add_co_u32_e32 v4, vcc, 0x36000, v82
	s_nop 1
	v_addc_co_u32_e32 v5, vcc, 0, v83, vcc
	global_store_dword v[4:5], v3, off offset:64
.LBB0_620:
	s_or_b64 exec, exec, s[8:9]
	v_mul_f32_e32 v3, v23, v2
	s_waitcnt lgkmcnt(0)
	s_nop 3
	v_mov_b32_dpp v4, v3 quad_perm:[1,0,3,2] row_mask:0xf bank_mask:0xf
	s_and_saveexec_b64 s[8:9], s[4:5]
	s_cbranch_execz .LBB0_622
	s_waitcnt lgkmcnt(0)
	v_cvt_pk_bf16_f32 v3, v3, v4
	v_add_co_u32_e32 v4, vcc, 0x36000, v82
	s_nop 1
	v_addc_co_u32_e32 v5, vcc, 0, v83, vcc
	global_store_dword v[4:5], v3, off offset:128
.LBB0_622:
	s_or_b64 exec, exec, s[8:9]
	v_mul_f32_e32 v2, v7, v2
	s_nop 3
	v_mov_b32_dpp v3, v2 quad_perm:[1,0,3,2] row_mask:0xf bank_mask:0xf
	s_and_saveexec_b64 s[8:9], s[4:5]
	s_cbranch_execz .LBB0_624
	s_waitcnt lgkmcnt(0)
	v_cvt_pk_bf16_f32 v4, v2, v3
	v_add_co_u32_e32 v2, vcc, 0x36000, v82
	s_nop 1
	v_addc_co_u32_e32 v3, vcc, 0, v83, vcc
	global_store_dword v[2:3], v4, off offset:192
.LBB0_624:
	s_or_b64 exec, exec, s[8:9]
	v_rcp_f32_e32 v2, v76
	s_waitcnt lgkmcnt(0)
	v_mul_f32_e32 v3, v40, v2
	s_nop 3
	v_mov_b32_dpp v4, v3 quad_perm:[1,0,3,2] row_mask:0xf bank_mask:0xf
	s_and_saveexec_b64 s[8:9], s[4:5]
	s_cbranch_execz .LBB0_626
	s_waitcnt lgkmcnt(0)
	v_cvt_pk_bf16_f32 v3, v3, v4
	v_add_co_u32_e32 v4, vcc, 0x3c000, v82
	s_nop 1
	v_addc_co_u32_e32 v5, vcc, 0, v83, vcc
	global_store_dword v[4:5], v3, off
.LBB0_626:
	s_or_b64 exec, exec, s[8:9]
	v_mul_f32_e32 v3, v56, v2
	s_waitcnt lgkmcnt(0)
	s_nop 3
	v_mov_b32_dpp v4, v3 quad_perm:[1,0,3,2] row_mask:0xf bank_mask:0xf
	s_and_saveexec_b64 s[8:9], s[4:5]
	s_cbranch_execz .LBB0_628
	s_waitcnt lgkmcnt(0)
	v_cvt_pk_bf16_f32 v3, v3, v4
	v_add_co_u32_e32 v4, vcc, 0x3c000, v82
	s_nop 1
	v_addc_co_u32_e32 v5, vcc, 0, v83, vcc
	global_store_dword v[4:5], v3, off offset:64
.LBB0_628:
	s_or_b64 exec, exec, s[8:9]
	v_mul_f32_e32 v3, v24, v2
	s_waitcnt lgkmcnt(0)
	s_nop 3
	v_mov_b32_dpp v4, v3 quad_perm:[1,0,3,2] row_mask:0xf bank_mask:0xf
	s_and_saveexec_b64 s[8:9], s[4:5]
	s_cbranch_execz .LBB0_630
	s_waitcnt lgkmcnt(0)
	v_cvt_pk_bf16_f32 v3, v3, v4
	v_add_co_u32_e32 v4, vcc, 0x3c000, v82
	s_nop 1
	v_addc_co_u32_e32 v5, vcc, 0, v83, vcc
	global_store_dword v[4:5], v3, off offset:128
; __device__ __forceinline__ unsigned cvt_pk_bf16(float lo, float hi) { unsigned r; asm volatile("v_cvt_pk_bf16_f32 %0, %1, %2" : "=v"(r) : "v"(lo), "v"(hi)); return r; }
; __device__ __forceinline__ int crow(int r, int hi) { return (r & 3) + 8 * (r >> 2) + 4 * hi; }
; __device__ __forceinline__ int crow(int r, int hi) { return (r & 3) + 8 * (r >> 2) + 4 * hi; }
; __device__ __forceinline__ void block(const BlockRef& cur, const BlockRef& nxt, lptr lds, Seam& S) {
;     ...
;     for (int r = 0; r < 16; ++r) { const int orow = crow(r, hi);
; #pragma unroll
;         for (int d0 = 0; d0 < 4; ++d0) { const float v = o[d0][r] * rli[r];
;             const float vn = __shfl_xor(v, 1);
;             if ((r32 & 1) == 0) *(unsigned*)(Ow + (size_t)orow * KM + d0 * 32 + r32) = cvt_pk_bf16(v, vn); } }
.LBB0_630:
	s_or_b64 exec, exec, s[8:9]
	v_mul_f32_e32 v2, v8, v2
	s_nop 3
	v_mov_b32_dpp v3, v2 quad_perm:[1,0,3,2] row_mask:0xf bank_mask:0xf
	s_and_saveexec_b64 s[8:9], s[4:5]
	s_cbranch_execz .LBB0_632
	s_waitcnt lgkmcnt(0)
	v_cvt_pk_bf16_f32 v4, v2, v3
	v_add_co_u32_e32 v2, vcc, 0x3c000, v82
	s_nop 1
	v_addc_co_u32_e32 v3, vcc, 0, v83, vcc
	global_store_dword v[2:3], v4, off offset:192
.LBB0_632:
	s_or_b64 exec, exec, s[8:9]
	v_rcp_f32_e32 v2, v77
	s_waitcnt lgkmcnt(0)
	v_mul_f32_e32 v3, v41, v2
	s_nop 3
	v_mov_b32_dpp v4, v3 quad_perm:[1,0,3,2] row_mask:0xf bank_mask:0xf
	s_and_saveexec_b64 s[8:9], s[4:5]
	s_cbranch_execz .LBB0_634
	s_waitcnt lgkmcnt(0)
	v_cvt_pk_bf16_f32 v3, v3, v4
	v_add_co_u32_e32 v4, vcc, 0x42000, v82
	s_nop 1
	v_addc_co_u32_e32 v5, vcc, 0, v83, vcc
	global_store_dword v[4:5], v3, off
.LBB0_634:
	s_or_b64 exec, exec, s[8:9]
	v_mul_f32_e32 v3, v57, v2
	s_waitcnt lgkmcnt(0)
	s_nop 3
	v_mov_b32_dpp v4, v3 quad_perm:[1,0,3,2] row_mask:0xf bank_mask:0xf
	s_and_saveexec_b64 s[8:9], s[4:5]
	s_cbranch_execz .LBB0_636
	s_waitcnt lgkmcnt(0)
	v_cvt_pk_bf16_f32 v3, v3, v4
	v_add_co_u32_e32 v4, vcc, 0x42000, v82
	s_nop 1
	v_addc_co_u32_e32 v5, vcc, 0, v83, vcc
	global_store_dword v[4:5], v3, off offset:64
.LBB0_636:
	s_or_b64 exec, exec, s[8:9]
	v_mul_f32_e32 v3, v25, v2
	s_waitcnt lgkmcnt(0)
	s_nop 3
	v_mov_b32_dpp v4, v3 quad_perm:[1,0,3,2] row_mask:0xf bank_mask:0xf
	s_and_saveexec_b64 s[8:9], s[4:5]
	s_cbranch_execz .LBB0_638
	s_waitcnt lgkmcnt(0)
	v_cvt_pk_bf16_f32 v3, v3, v4
	v_add_co_u32_e32 v4, vcc, 0x42000, v82
	s_nop 1
	v_addc_co_u32_e32 v5, vcc, 0, v83, vcc
	global_store_dword v[4:5], v3, off offset:128
.LBB0_638:
	s_or_b64 exec, exec, s[8:9]
	v_mul_f32_e32 v2, v9, v2
	s_nop 3
	v_mov_b32_dpp v3, v2 quad_perm:[1,0,3,2] row_mask:0xf bank_mask:0xf
	s_and_saveexec_b64 s[8:9], s[4:5]
	s_cbranch_execz .LBB0_640
	s_waitcnt lgkmcnt(0)
	v_cvt_pk_bf16_f32 v4, v2, v3
	v_add_co_u32_e32 v2, vcc, 0x42000, v82
	s_nop 1
	v_addc_co_u32_e32 v3, vcc, 0, v83, vcc
	global_store_dword v[2:3], v4, off offset:192
.LBB0_640:
	s_or_b64 exec, exec, s[8:9]
	v_rcp_f32_e32 v2, v70
	s_waitcnt lgkmcnt(0)
	v_mul_f32_e32 v3, v42, v2
	s_nop 3
	v_mov_b32_dpp v4, v3 quad_perm:[1,0,3,2] row_mask:0xf bank_mask:0xf
	s_and_saveexec_b64 s[8:9], s[4:5]
	s_cbranch_execz .LBB0_642
	s_waitcnt lgkmcnt(0)
	v_cvt_pk_bf16_f32 v3, v3, v4
	v_add_co_u32_e32 v4, vcc, 0x60000, v82
	s_nop 1
	v_addc_co_u32_e32 v5, vcc, 0, v83, vcc
	global_store_dword v[4:5], v3, off
.LBB0_642:
	s_or_b64 exec, exec, s[8:9]
	v_mul_f32_e32 v3, v58, v2
	s_waitcnt lgkmcnt(0)
	s_nop 3
	v_mov_b32_dpp v4, v3 quad_perm:[1,0,3,2] row_mask:0xf bank_mask:0xf
	s_and_saveexec_b64 s[8:9], s[4:5]
	s_cbranch_execz .LBB0_644
	s_waitcnt lgkmcnt(0)
	v_cvt_pk_bf16_f32 v3, v3, v4
	v_add_co_u32_e32 v4, vcc, 0x60000, v82
	s_nop 1
	v_addc_co_u32_e32 v5, vcc, 0, v83, vcc
	global_store_dword v[4:5], v3, off offset:64
.LBB0_644:
	s_or_b64 exec, exec, s[8:9]
	v_mul_f32_e32 v3, v26, v2
	s_waitcnt lgkmcnt(0)
	s_nop 3
	v_mov_b32_dpp v4, v3 quad_perm:[1,0,3,2] row_mask:0xf bank_mask:0xf
	s_and_saveexec_b64 s[8:9], s[4:5]
	s_cbranch_execz .LBB0_646
	s_waitcnt lgkmcnt(0)
	v_cvt_pk_bf16_f32 v3, v3, v4
	v_add_co_u32_e32 v4, vcc, 0x60000, v82
	s_nop 1
	v_addc_co_u32_e32 v5, vcc, 0, v83, vcc
	global_store_dword v[4:5], v3, off offset:128
.LBB0_646:
	s_or_b64 exec, exec, s[8:9]
	v_mul_f32_e32 v2, v10, v2
	s_nop 3
	v_mov_b32_dpp v3, v2 quad_perm:[1,0,3,2] row_mask:0xf bank_mask:0xf
	s_and_saveexec_b64 s[8:9], s[4:5]
	s_cbranch_execz .LBB0_648
	s_waitcnt lgkmcnt(0)
	v_cvt_pk_bf16_f32 v4, v2, v3
	v_add_co_u32_e32 v2, vcc, 0x60000, v82
	s_nop 1
	v_addc_co_u32_e32 v3, vcc, 0, v83, vcc
	global_store_dword v[2:3], v4, off offset:192
.LBB0_648:
	s_or_b64 exec, exec, s[8:9]
	v_rcp_f32_e32 v2, v71
	s_waitcnt lgkmcnt(0)
	v_mul_f32_e32 v3, v43, v2
	s_nop 3
	v_mov_b32_dpp v4, v3 quad_perm:[1,0,3,2] row_mask:0xf bank_mask:0xf
	s_and_saveexec_b64 s[8:9], s[4:5]
	s_cbranch_execz .LBB0_650
	s_waitcnt lgkmcnt(0)
	v_cvt_pk_bf16_f32 v3, v3, v4
	v_add_co_u32_e32 v4, vcc, 0x66000, v82
	s_nop 1
	v_addc_co_u32_e32 v5, vcc, 0, v83, vcc
	global_store_dword v[4:5], v3, off
.LBB0_650:
	s_or_b64 exec, exec, s[8:9]
	v_mul_f32_e32 v3, v59, v2
	s_waitcnt lgkmcnt(0)
	s_nop 3
	v_mov_b32_dpp v4, v3 quad_perm:[1,0,3,2] row_mask:0xf bank_mask:0xf
	s_and_saveexec_b64 s[8:9], s[4:5]
	s_cbranch_execz .LBB0_652
	s_waitcnt lgkmcnt(0)
	v_cvt_pk_bf16_f32 v3, v3, v4
	v_add_co_u32_e32 v4, vcc, 0x66000, v82
	s_nop 1
	v_addc_co_u32_e32 v5, vcc, 0, v83, vcc
	global_store_dword v[4:5], v3, off offset:64
.LBB0_652:
	s_or_b64 exec, exec, s[8:9]
	v_mul_f32_e32 v3, v27, v2
	s_waitcnt lgkmcnt(0)
	s_nop 3
	v_mov_b32_dpp v4, v3 quad_perm:[1,0,3,2] row_mask:0xf bank_mask:0xf
	s_and_saveexec_b64 s[8:9], s[4:5]
	s_cbranch_execz .LBB0_654
	s_waitcnt lgkmcnt(0)
	v_cvt_pk_bf16_f32 v3, v3, v4
	v_add_co_u32_e32 v4, vcc, 0x66000, v82
	s_nop 1
	v_addc_co_u32_e32 v5, vcc, 0, v83, vcc
	global_store_dword v[4:5], v3, off offset:128
.LBB0_654:
	s_or_b64 exec, exec, s[8:9]
	v_mul_f32_e32 v2, v11, v2
	s_nop 3
	v_mov_b32_dpp v3, v2 quad_perm:[1,0,3,2] row_mask:0xf bank_mask:0xf
	s_and_saveexec_b64 s[8:9], s[4:5]
	s_cbranch_execz .LBB0_656
	s_waitcnt lgkmcnt(0)
	v_cvt_pk_bf16_f32 v4, v2, v3
	v_add_co_u32_e32 v2, vcc, 0x66000, v82
	s_nop 1
	v_addc_co_u32_e32 v3, vcc, 0, v83, vcc
	global_store_dword v[2:3], v4, off offset:192
.LBB0_656:
	s_or_b64 exec, exec, s[8:9]
	v_rcp_f32_e32 v2, v72
	s_waitcnt lgkmcnt(0)
	v_mul_f32_e32 v3, v44, v2
	s_nop 3
	v_mov_b32_dpp v4, v3 quad_perm:[1,0,3,2] row_mask:0xf bank_mask:0xf
	s_and_saveexec_b64 s[8:9], s[4:5]
	s_cbranch_execz .LBB0_658
	s_waitcnt lgkmcnt(0)
	v_cvt_pk_bf16_f32 v3, v3, v4
	v_add_co_u32_e32 v4, vcc, 0x6c000, v82
	s_nop 1
	v_addc_co_u32_e32 v5, vcc, 0, v83, vcc
	global_store_dword v[4:5], v3, off
; __device__ __forceinline__ unsigned cvt_pk_bf16(float lo, float hi) { unsigned r; asm volatile("v_cvt_pk_bf16_f32 %0, %1, %2" : "=v"(r) : "v"(lo), "v"(hi)); return r; }
; __device__ __forceinline__ int crow(int r, int hi) { return (r & 3) + 8 * (r >> 2) + 4 * hi; }
; __device__ __forceinline__ int crow(int r, int hi) { return (r & 3) + 8 * (r >> 2) + 4 * hi; }
; __device__ __forceinline__ void block(const BlockRef& cur, const BlockRef& nxt, lptr lds, Seam& S) {
;     ...
;     for (int r = 0; r < 16; ++r) { const int orow = crow(r, hi);
; #pragma unroll
;         for (int d0 = 0; d0 < 4; ++d0) { const float v = o[d0][r] * rli[r];
;             const float vn = __shfl_xor(v, 1);
;             if ((r32 & 1) == 0) *(unsigned*)(Ow + (size_t)orow * KM + d0 * 32 + r32) = cvt_pk_bf16(v, vn); } }
.LBB0_658:
	s_or_b64 exec, exec, s[8:9]
	v_mul_f32_e32 v3, v60, v2
	s_waitcnt lgkmcnt(0)
	s_nop 3
	v_mov_b32_dpp v4, v3 quad_perm:[1,0,3,2] row_mask:0xf bank_mask:0xf
	s_and_saveexec_b64 s[8:9], s[4:5]
	s_cbranch_execz .LBB0_660
	s_waitcnt lgkmcnt(0)
	v_cvt_pk_bf16_f32 v3, v3, v4
	v_add_co_u32_e32 v4, vcc, 0x6c000, v82
	s_nop 1
	v_addc_co_u32_e32 v5, vcc, 0, v83, vcc
	global_store_dword v[4:5], v3, off offset:64
.LBB0_660:
	s_or_b64 exec, exec, s[8:9]
	v_mul_f32_e32 v3, v28, v2
	s_waitcnt lgkmcnt(0)
	s_nop 3
	v_mov_b32_dpp v4, v3 quad_perm:[1,0,3,2] row_mask:0xf bank_mask:0xf
	s_and_saveexec_b64 s[8:9], s[4:5]
	s_cbranch_execz .LBB0_662
	s_waitcnt lgkmcnt(0)
	v_cvt_pk_bf16_f32 v3, v3, v4
	v_add_co_u32_e32 v4, vcc, 0x6c000, v82
	s_nop 1
	v_addc_co_u32_e32 v5, vcc, 0, v83, vcc
	global_store_dword v[4:5], v3, off offset:128
.LBB0_662:
	s_or_b64 exec, exec, s[8:9]
	v_mul_f32_e32 v2, v12, v2
	s_nop 3
	v_mov_b32_dpp v3, v2 quad_perm:[1,0,3,2] row_mask:0xf bank_mask:0xf
	s_and_saveexec_b64 s[8:9], s[4:5]
	s_cbranch_execz .LBB0_664
	s_waitcnt lgkmcnt(0)
	v_cvt_pk_bf16_f32 v4, v2, v3
	v_add_co_u32_e32 v2, vcc, 0x6c000, v82
	s_nop 1
	v_addc_co_u32_e32 v3, vcc, 0, v83, vcc
	global_store_dword v[2:3], v4, off offset:192
.LBB0_664:
	s_or_b64 exec, exec, s[8:9]
	v_rcp_f32_e32 v2, v73
	s_waitcnt lgkmcnt(0)
	v_mul_f32_e32 v3, v45, v2
	s_nop 3
	v_mov_b32_dpp v4, v3 quad_perm:[1,0,3,2] row_mask:0xf bank_mask:0xf
	s_and_saveexec_b64 s[8:9], s[4:5]
	s_cbranch_execz .LBB0_666
	s_waitcnt lgkmcnt(0)
	v_cvt_pk_bf16_f32 v3, v3, v4
	v_add_co_u32_e32 v4, vcc, 0x72000, v82
	s_nop 1
	v_addc_co_u32_e32 v5, vcc, 0, v83, vcc
	global_store_dword v[4:5], v3, off
.LBB0_666:
	s_or_b64 exec, exec, s[8:9]
	v_mul_f32_e32 v3, v61, v2
	s_waitcnt lgkmcnt(0)
	s_nop 3
	v_mov_b32_dpp v4, v3 quad_perm:[1,0,3,2] row_mask:0xf bank_mask:0xf
	s_and_saveexec_b64 s[8:9], s[4:5]
	s_cbranch_execz .LBB0_668
	s_waitcnt lgkmcnt(0)
	v_cvt_pk_bf16_f32 v3, v3, v4
	v_add_co_u32_e32 v4, vcc, 0x72000, v82
	s_nop 1
	v_addc_co_u32_e32 v5, vcc, 0, v83, vcc
	global_store_dword v[4:5], v3, off offset:64
.LBB0_668:
	s_or_b64 exec, exec, s[8:9]
	v_mul_f32_e32 v3, v29, v2
	s_waitcnt lgkmcnt(0)
	s_nop 3
	v_mov_b32_dpp v4, v3 quad_perm:[1,0,3,2] row_mask:0xf bank_mask:0xf
	s_and_saveexec_b64 s[8:9], s[4:5]
	s_cbranch_execz .LBB0_670
	s_waitcnt lgkmcnt(0)
	v_cvt_pk_bf16_f32 v3, v3, v4
	v_add_co_u32_e32 v4, vcc, 0x72000, v82
	s_nop 1
	v_addc_co_u32_e32 v5, vcc, 0, v83, vcc
	global_store_dword v[4:5], v3, off offset:128
.LBB0_670:
	s_or_b64 exec, exec, s[8:9]
	v_mul_f32_e32 v2, v13, v2
	s_nop 3
	v_mov_b32_dpp v3, v2 quad_perm:[1,0,3,2] row_mask:0xf bank_mask:0xf
	s_and_saveexec_b64 s[8:9], s[4:5]
	s_cbranch_execz .LBB0_672
	s_waitcnt lgkmcnt(0)
	v_cvt_pk_bf16_f32 v4, v2, v3
	v_add_co_u32_e32 v2, vcc, 0x72000, v82
	s_nop 1
	v_addc_co_u32_e32 v3, vcc, 0, v83, vcc
	global_store_dword v[2:3], v4, off offset:192
.LBB0_672:
	s_or_b64 exec, exec, s[8:9]
	v_rcp_f32_e32 v2, v66
	s_waitcnt lgkmcnt(0)
	v_mul_f32_e32 v3, v46, v2
	s_nop 3
	v_mov_b32_dpp v4, v3 quad_perm:[1,0,3,2] row_mask:0xf bank_mask:0xf
	s_and_saveexec_b64 s[8:9], s[4:5]
	s_cbranch_execz .LBB0_674
	s_waitcnt lgkmcnt(0)
	v_cvt_pk_bf16_f32 v3, v3, v4
	v_add_co_u32_e32 v4, vcc, 0x90000, v82
	s_nop 1
	v_addc_co_u32_e32 v5, vcc, 0, v83, vcc
	global_store_dword v[4:5], v3, off
.LBB0_674:
	s_or_b64 exec, exec, s[8:9]
	v_mul_f32_e32 v3, v62, v2
	s_waitcnt lgkmcnt(0)
	s_nop 3
	v_mov_b32_dpp v4, v3 quad_perm:[1,0,3,2] row_mask:0xf bank_mask:0xf
	s_and_saveexec_b64 s[8:9], s[4:5]
	s_cbranch_execz .LBB0_676
	s_waitcnt lgkmcnt(0)
	v_cvt_pk_bf16_f32 v3, v3, v4
	v_add_co_u32_e32 v4, vcc, 0x90000, v82
	s_nop 1
	v_addc_co_u32_e32 v5, vcc, 0, v83, vcc
	global_store_dword v[4:5], v3, off offset:64
.LBB0_676:
	s_or_b64 exec, exec, s[8:9]
	v_mul_f32_e32 v3, v30, v2
	s_waitcnt lgkmcnt(0)
	s_nop 3
	v_mov_b32_dpp v4, v3 quad_perm:[1,0,3,2] row_mask:0xf bank_mask:0xf
	s_and_saveexec_b64 s[8:9], s[4:5]
	s_cbranch_execz .LBB0_678
	s_waitcnt lgkmcnt(0)
	v_cvt_pk_bf16_f32 v3, v3, v4
	v_add_co_u32_e32 v4, vcc, 0x90000, v82
	s_nop 1
	v_addc_co_u32_e32 v5, vcc, 0, v83, vcc
	global_store_dword v[4:5], v3, off offset:128
.LBB0_678:
	s_or_b64 exec, exec, s[8:9]
	v_mul_f32_e32 v2, v14, v2
	s_nop 3
	v_mov_b32_dpp v3, v2 quad_perm:[1,0,3,2] row_mask:0xf bank_mask:0xf
	s_and_saveexec_b64 s[8:9], s[4:5]
	s_cbranch_execz .LBB0_680
	s_waitcnt lgkmcnt(0)
	v_cvt_pk_bf16_f32 v4, v2, v3
	v_add_co_u32_e32 v2, vcc, 0x90000, v82
	s_nop 1
	v_addc_co_u32_e32 v3, vcc, 0, v83, vcc
	global_store_dword v[2:3], v4, off offset:192
; __device__ __forceinline__ unsigned cvt_pk_bf16(float lo, float hi) { unsigned r; asm volatile("v_cvt_pk_bf16_f32 %0, %1, %2" : "=v"(r) : "v"(lo), "v"(hi)); return r; }
; __device__ __forceinline__ int crow(int r, int hi) { return (r & 3) + 8 * (r >> 2) + 4 * hi; }
; __device__ __forceinline__ int crow(int r, int hi) { return (r & 3) + 8 * (r >> 2) + 4 * hi; }
; __device__ __forceinline__ void block(const BlockRef& cur, const BlockRef& nxt, lptr lds, Seam& S) {
;     ...
;     for (int r = 0; r < 16; ++r) { const int orow = crow(r, hi);
; #pragma unroll
;         for (int d0 = 0; d0 < 4; ++d0) { const float v = o[d0][r] * rli[r];
;             const float vn = __shfl_xor(v, 1);
;             if ((r32 & 1) == 0) *(unsigned*)(Ow + (size_t)orow * KM + d0 * 32 + r32) = cvt_pk_bf16(v, vn); } }
.LBB0_680:
	s_or_b64 exec, exec, s[8:9]
	v_rcp_f32_e32 v2, v67
	s_waitcnt lgkmcnt(0)
	v_mul_f32_e32 v3, v47, v2
	s_nop 3
	v_mov_b32_dpp v4, v3 quad_perm:[1,0,3,2] row_mask:0xf bank_mask:0xf
	s_and_saveexec_b64 s[8:9], s[4:5]
	s_cbranch_execz .LBB0_682
	s_waitcnt lgkmcnt(0)
	v_cvt_pk_bf16_f32 v3, v3, v4
	v_add_co_u32_e32 v4, vcc, 0x96000, v82
	s_nop 1
	v_addc_co_u32_e32 v5, vcc, 0, v83, vcc
	global_store_dword v[4:5], v3, off
.LBB0_682:
	s_or_b64 exec, exec, s[8:9]
	v_mul_f32_e32 v3, v63, v2
	s_waitcnt lgkmcnt(0)
	s_nop 3
	v_mov_b32_dpp v4, v3 quad_perm:[1,0,3,2] row_mask:0xf bank_mask:0xf
	s_and_saveexec_b64 s[8:9], s[4:5]
	s_cbranch_execz .LBB0_684
	s_waitcnt lgkmcnt(0)
	v_cvt_pk_bf16_f32 v3, v3, v4
	v_add_co_u32_e32 v4, vcc, 0x96000, v82
	s_nop 1
	v_addc_co_u32_e32 v5, vcc, 0, v83, vcc
	global_store_dword v[4:5], v3, off offset:64
.LBB0_684:
	s_or_b64 exec, exec, s[8:9]
	v_mul_f32_e32 v3, v31, v2
	s_waitcnt lgkmcnt(0)
	s_nop 3
	v_mov_b32_dpp v4, v3 quad_perm:[1,0,3,2] row_mask:0xf bank_mask:0xf
	s_and_saveexec_b64 s[8:9], s[4:5]
	s_cbranch_execz .LBB0_686
	s_waitcnt lgkmcnt(0)
	v_cvt_pk_bf16_f32 v3, v3, v4
	v_add_co_u32_e32 v4, vcc, 0x96000, v82
	s_nop 1
	v_addc_co_u32_e32 v5, vcc, 0, v83, vcc
	global_store_dword v[4:5], v3, off offset:128
.LBB0_686:
	s_or_b64 exec, exec, s[8:9]
	v_mul_f32_e32 v2, v15, v2
	s_nop 3
	v_mov_b32_dpp v3, v2 quad_perm:[1,0,3,2] row_mask:0xf bank_mask:0xf
	s_and_saveexec_b64 s[8:9], s[4:5]
	s_cbranch_execz .LBB0_688
	s_waitcnt lgkmcnt(0)
	v_cvt_pk_bf16_f32 v4, v2, v3
	v_add_co_u32_e32 v2, vcc, 0x96000, v82
	s_nop 1
	v_addc_co_u32_e32 v3, vcc, 0, v83, vcc
	global_store_dword v[2:3], v4, off offset:192
.LBB0_688:
	s_or_b64 exec, exec, s[8:9]
	v_rcp_f32_e32 v2, v68
	s_waitcnt lgkmcnt(0)
	v_mul_f32_e32 v3, v48, v2
	s_nop 3
	v_mov_b32_dpp v4, v3 quad_perm:[1,0,3,2] row_mask:0xf bank_mask:0xf
	s_and_saveexec_b64 s[8:9], s[4:5]
	s_cbranch_execz .LBB0_690
	s_waitcnt lgkmcnt(0)
	v_cvt_pk_bf16_f32 v3, v3, v4
	v_add_co_u32_e32 v4, vcc, 0x9c000, v82
	s_nop 1
	v_addc_co_u32_e32 v5, vcc, 0, v83, vcc
	global_store_dword v[4:5], v3, off
.LBB0_690:
	s_or_b64 exec, exec, s[8:9]
	v_mul_f32_e32 v3, v64, v2
	s_waitcnt lgkmcnt(0)
	s_nop 3
	v_mov_b32_dpp v4, v3 quad_perm:[1,0,3,2] row_mask:0xf bank_mask:0xf
	s_and_saveexec_b64 s[8:9], s[4:5]
	s_cbranch_execz .LBB0_692
	s_waitcnt lgkmcnt(0)
	v_cvt_pk_bf16_f32 v3, v3, v4
	v_add_co_u32_e32 v4, vcc, 0x9c000, v82
	s_nop 1
	v_addc_co_u32_e32 v5, vcc, 0, v83, vcc
	global_store_dword v[4:5], v3, off offset:64
.LBB0_692:
	s_or_b64 exec, exec, s[8:9]
	v_mul_f32_e32 v3, v32, v2
	s_waitcnt lgkmcnt(0)
	s_nop 3
	v_mov_b32_dpp v4, v3 quad_perm:[1,0,3,2] row_mask:0xf bank_mask:0xf
	s_and_saveexec_b64 s[8:9], s[4:5]
	s_cbranch_execz .LBB0_694
	s_waitcnt lgkmcnt(0)
	v_cvt_pk_bf16_f32 v3, v3, v4
	v_add_co_u32_e32 v4, vcc, 0x9c000, v82
	s_nop 1
	v_addc_co_u32_e32 v5, vcc, 0, v83, vcc
	global_store_dword v[4:5], v3, off offset:128
.LBB0_694:
	s_or_b64 exec, exec, s[8:9]
	v_mul_f32_e32 v2, v16, v2
	s_nop 3
	v_mov_b32_dpp v3, v2 quad_perm:[1,0,3,2] row_mask:0xf bank_mask:0xf
	s_and_saveexec_b64 s[8:9], s[4:5]
	s_cbranch_execz .LBB0_696
	s_waitcnt lgkmcnt(0)
	v_cvt_pk_bf16_f32 v4, v2, v3
	v_add_co_u32_e32 v2, vcc, 0x9c000, v82
	s_nop 1
	v_addc_co_u32_e32 v3, vcc, 0, v83, vcc
	global_store_dword v[2:3], v4, off offset:192
.LBB0_696:
	s_or_b64 exec, exec, s[8:9]
	v_rcp_f32_e32 v2, v69
	s_waitcnt lgkmcnt(0)
	v_mul_f32_e32 v3, v49, v2
	s_nop 3
	v_mov_b32_dpp v4, v3 quad_perm:[1,0,3,2] row_mask:0xf bank_mask:0xf
	s_and_saveexec_b64 s[8:9], s[4:5]
	s_cbranch_execz .LBB0_698
	s_waitcnt lgkmcnt(0)
	v_cvt_pk_bf16_f32 v3, v3, v4
	v_add_co_u32_e32 v4, vcc, 0xa2000, v82
	s_nop 1
	v_addc_co_u32_e32 v5, vcc, 0, v83, vcc
	global_store_dword v[4:5], v3, off
.LBB0_698:
	s_or_b64 exec, exec, s[8:9]
	v_mul_f32_e32 v3, v65, v2
	s_waitcnt lgkmcnt(0)
	s_nop 3
	v_mov_b32_dpp v4, v3 quad_perm:[1,0,3,2] row_mask:0xf bank_mask:0xf
	s_and_saveexec_b64 s[8:9], s[4:5]
	s_cbranch_execz .LBB0_700
	s_waitcnt lgkmcnt(0)
	v_cvt_pk_bf16_f32 v3, v3, v4
	v_add_co_u32_e32 v4, vcc, 0xa2000, v82
	s_nop 1
	v_addc_co_u32_e32 v5, vcc, 0, v83, vcc
	global_store_dword v[4:5], v3, off offset:64
.LBB0_700:
	s_or_b64 exec, exec, s[8:9]
	v_mul_f32_e32 v3, v33, v2
	s_waitcnt lgkmcnt(0)
	s_nop 3
	v_mov_b32_dpp v4, v3 quad_perm:[1,0,3,2] row_mask:0xf bank_mask:0xf
	s_and_saveexec_b64 s[8:9], s[4:5]
	s_cbranch_execz .LBB0_702
	s_waitcnt lgkmcnt(0)
	v_cvt_pk_bf16_f32 v3, v3, v4
	v_add_co_u32_e32 v4, vcc, 0xa2000, v82
	s_nop 1
	v_addc_co_u32_e32 v5, vcc, 0, v83, vcc
	global_store_dword v[4:5], v3, off offset:128
.LBB0_702:
	s_or_b64 exec, exec, s[8:9]
	v_mul_f32_e32 v2, v17, v2
	s_nop 3
	v_mov_b32_dpp v3, v2 quad_perm:[1,0,3,2] row_mask:0xf bank_mask:0xf
	s_and_saveexec_b64 s[8:9], s[4:5]
	s_cbranch_execz .LBB0_704
	s_waitcnt lgkmcnt(0)
	v_cvt_pk_bf16_f32 v4, v2, v3
	v_add_co_u32_e32 v2, vcc, 0xa2000, v82
	s_nop 1
	v_addc_co_u32_e32 v3, vcc, 0, v83, vcc
	global_store_dword v[2:3], v4, off offset:192
